# attention tile loop: second sub-tile's first two groups of score-operand reads (K0/Q0, K1/Q1) issued inside the first sub-tile's map-1 PV MFMAs
# baseline (speedup 1.0000x reference)
; #define LAS __attribute__((address_space(3)))
; __device__ __forceinline__ void dattn_unit(LAS unsigned char* lds, int b, int h, int qb, const bf16* Q, const bf16* K, const bf16* V, bf16* YB, float lam, const float* subg, float oml, int tid) {
;     ...
;                 const LAS bf16* kp = Ks + (32 * sub + ql) * 72 + hi * 8;
;                 bf16x8 ka = *(const LAS bf16x8*)kp, kb = *(const LAS bf16x8*)(kp + 64 * 72), qa = qsp[0], qb = qsp[4 * 64];
;                 __builtin_amdgcn_sched_group_barrier(0x100, 4, 0);
; #pragma unroll
;                 for (int ks = 0; ks < 4; ++ks) { bf16x8 ka2 = ka, kb2 = kb, qa2 = qa, qb2 = qb;
;                     if (ks < 3) { ka2 = *(const LAS bf16x8*)(kp + (ks + 1) * 16); kb2 = *(const LAS bf16x8*)(kp + 64 * 72 + (ks + 1) * 16); qa2 = qsp[(ks + 1) * 64]; qb2 = qsp[(4 + ks + 1) * 64];
;     ...
;             for (int cb = 0; cb < 4; ++cb) { const LAS bf16* vp = Vt + (32 * cb + ql) * 72 + 32 * sub + 4 * hi;
;                 const v2u a0 = *(const LAS v2u*)(vp), a1 = *(const LAS v2u*)(vp + 8), a2 = *(const LAS v2u*)(vp + 16), a3 = *(const LAS v2u*)(vp + 24);
;                 const v4u f0 = {a0.x, a0.y, a1.x, a1.y}, f1 = {a2.x, a2.y, a3.x, a3.y};
;                 o[0][cb] = __builtin_amdgcn_mfma_f32_32x32x16_bf16(__builtin_bit_cast(bf16x8, f0), pA0, o[0][cb], 0, 0, 0);
;                 o[1][cb] = __builtin_amdgcn_mfma_f32_32x32x16_bf16(__builtin_bit_cast(bf16x8, f0), pA1, o[1][cb], 0, 0, 0);
;                 o[0][cb] = __builtin_amdgcn_mfma_f32_32x32x16_bf16(__builtin_bit_cast(bf16x8, f1), pB0, o[0][cb], 0, 0, 0);
;                 o[1][cb] = __builtin_amdgcn_mfma_f32_32x32x16_bf16(__builtin_bit_cast(bf16x8, f1), pB1, o[1][cb], 0, 0, 0); }
.LBB0_234:
	v_cvt_pk_bf16_f32 v152, v155, v129
	v_cvt_pk_bf16_f32 v153, v130, v131
	v_cvt_pk_bf16_f32 v154, v132, v156
	v_cvt_pk_bf16_f32 v155, v157, v158
	v_cvt_pk_bf16_f32 v130, v133, v134
	v_cvt_pk_bf16_f32 v131, v135, v136
	v_cvt_pk_bf16_f32 v132, v137, v138
	v_cvt_pk_bf16_f32 v133, v139, v140
	s_andn2_b64 vcc, exec, s[48:49]
	s_nop 0
	v_mfma_f32_32x32x16_bf16 v[64:79], v[228:231], v[152:155], v[64:79]
	ds_read_b128 v[138:141], v199 offset:4608
	v_mfma_f32_32x32x16_bf16 v[64:79], v[232:235], v[130:133], v[64:79]
	v_mfma_f32_32x32x16_bf16 v[32:47], v[236:239], v[152:155], v[32:47]
	v_mfma_f32_32x32x16_bf16 v[32:47], v[240:243], v[130:133], v[32:47]
	v_mfma_f32_32x32x16_bf16 v[96:111], v[220:223], v[152:155], v[96:111]
	ds_read_b128 v[218:221], v189
	ds_read_b128 v[222:225], v189 offset:4096
	v_mfma_f32_32x32x16_bf16 v[96:111], v[204:207], v[130:133], v[96:111]
	ds_read_b128 v[204:207], v199 offset:13824
	ds_read_b128 v[226:229], v199 offset:4640
	ds_read_b128 v[230:233], v199 offset:13856
	v_mfma_f32_32x32x16_bf16 v[0:15], v[212:215], v[152:155], v[0:15]
	ds_read_b128 v[234:237], v189 offset:1024
	ds_read_b128 v[238:241], v189 offset:5120
	v_mfma_f32_32x32x16_bf16 v[0:15], v[200:203], v[130:133], v[0:15]
	s_cbranch_vccnz .LBB0_236
	v_log_f32_e32 v129, v146
	s_nop 0
	v_max_f32_e32 v129, 0, v129
	v_exp_f32_e64 v130, -v129
	v_add_f32_e32 v190, v190, v129
	s_nop 1
	v_pk_mul_f32 v[126:127], v[130:131], v[126:127] op_sel_hi:[0,1]
	v_pk_mul_f32 v[124:125], v[130:131], v[124:125] op_sel_hi:[0,1]
	v_pk_mul_f32 v[122:123], v[130:131], v[122:123] op_sel_hi:[0,1]
	v_pk_mul_f32 v[120:121], v[130:131], v[120:121] op_sel_hi:[0,1]
	v_pk_mul_f32 v[118:119], v[130:131], v[118:119] op_sel_hi:[0,1]
	v_pk_mul_f32 v[116:117], v[130:131], v[116:117] op_sel_hi:[0,1]
	v_pk_mul_f32 v[114:115], v[130:131], v[114:115] op_sel_hi:[0,1]
	v_pk_mul_f32 v[112:113], v[130:131], v[112:113] op_sel_hi:[0,1]
	v_pk_mul_f32 v[94:95], v[130:131], v[94:95] op_sel_hi:[0,1]
	v_pk_mul_f32 v[92:93], v[130:131], v[92:93] op_sel_hi:[0,1]
	v_pk_mul_f32 v[90:91], v[130:131], v[90:91] op_sel_hi:[0,1]
	v_pk_mul_f32 v[88:89], v[130:131], v[88:89] op_sel_hi:[0,1]
	v_pk_mul_f32 v[86:87], v[130:131], v[86:87] op_sel_hi:[0,1]
	v_pk_mul_f32 v[84:85], v[130:131], v[84:85] op_sel_hi:[0,1]
	v_pk_mul_f32 v[82:83], v[130:131], v[82:83] op_sel_hi:[0,1]
	v_pk_mul_f32 v[80:81], v[130:131], v[80:81] op_sel_hi:[0,1]
	v_pk_mul_f32 v[62:63], v[130:131], v[62:63] op_sel_hi:[0,1]
	v_pk_mul_f32 v[60:61], v[130:131], v[60:61] op_sel_hi:[0,1]
	v_pk_mul_f32 v[58:59], v[130:131], v[58:59] op_sel_hi:[0,1]
	v_pk_mul_f32 v[56:57], v[130:131], v[56:57] op_sel_hi:[0,1]
	v_pk_mul_f32 v[54:55], v[130:131], v[54:55] op_sel_hi:[0,1]
	v_pk_mul_f32 v[52:53], v[130:131], v[52:53] op_sel_hi:[0,1]
	v_pk_mul_f32 v[50:51], v[130:131], v[50:51] op_sel_hi:[0,1]
	v_pk_mul_f32 v[48:49], v[130:131], v[48:49] op_sel_hi:[0,1]
	v_pk_mul_f32 v[30:31], v[130:131], v[30:31] op_sel_hi:[0,1]
	v_pk_mul_f32 v[28:29], v[130:131], v[28:29] op_sel_hi:[0,1]
	v_pk_mul_f32 v[26:27], v[130:131], v[26:27] op_sel_hi:[0,1]
	v_pk_mul_f32 v[24:25], v[130:131], v[24:25] op_sel_hi:[0,1]
	v_pk_mul_f32 v[22:23], v[130:131], v[22:23] op_sel_hi:[0,1]
	v_pk_mul_f32 v[20:21], v[130:131], v[20:21] op_sel_hi:[0,1]
	v_pk_mul_f32 v[18:19], v[130:131], v[18:19] op_sel_hi:[0,1]
	v_pk_mul_f32 v[16:17], v[130:131], v[16:17] op_sel_hi:[0,1]
	v_mul_f32_e32 v179, v179, v130

; #define LAS __attribute__((address_space(3)))
; __device__ __forceinline__ void dattn_unit(LAS unsigned char* lds, int b, int h, int qb, const bf16* Q, const bf16* K, const bf16* V, bf16* YB, float lam, const float* subg, float oml, int tid) {
;     ...
;             if (kvbase + 32 * sub > qmax) continue;
;             const bool need_bm = kvbase + 32 * sub + 31 + 113 > qmin;
;             LAS bf16x8* qsp = qs; asm volatile("" : "+v"(qsp));
;             f32x16 s0, s1;
; #pragma unroll
;             for (int r = 0; r < 16; ++r) { s0[r] = -mref[0]; s1[r] = -mref[1]; }
;             {
;                 const LAS bf16* kp = Ks + (32 * sub + ql) * 72 + hi * 8;
;                 bf16x8 ka = *(const LAS bf16x8*)kp, kb = *(const LAS bf16x8*)(kp + 64 * 72), qa = qsp[0], qb = qsp[4 * 64];
;                 __builtin_amdgcn_sched_group_barrier(0x100, 4, 0);
; #pragma unroll
;                 for (int ks = 0; ks < 4; ++ks) { bf16x8 ka2 = ka, kb2 = kb, qa2 = qa, qb2 = qb;
;                     if (ks < 3) { ka2 = *(const LAS bf16x8*)(kp + (ks + 1) * 16); kb2 = *(const LAS bf16x8*)(kp + 64 * 72 + (ks + 1) * 16); qa2 = qsp[(ks + 1) * 64]; qb2 = qsp[(4 + ks + 1) * 64];
;                         __builtin_amdgcn_sched_group_barrier(0x100, 4, 0); }
;                     s0 = __builtin_amdgcn_mfma_f32_32x32x16_bf16(ka, qa, s0, 0, 0, 0);
;                     s1 = __builtin_amdgcn_mfma_f32_32x32x16_bf16(kb, qb, s1, 0, 0, 0);
;                     __builtin_amdgcn_sched_group_barrier(0x008, 2, 0);
;                     ka = ka2; kb = kb2; qa = qa2; qb = qb2; }
;             }
.LBB0_238:
	s_add_i32 s18, s58, 0xffffff70
	s_cmp_gt_i32 s18, s35
	s_cbranch_scc1 .LBB0_226
	v_xor_b32_e32 v144, 0x80000000, v190
	v_xor_b32_e32 v128, 0x80000000, v191
	v_mov_b32_e32 v145, v144
	v_mov_b64_e32 v[146:147], v[144:145]
	v_mov_b64_e32 v[148:149], v[144:145]
	v_mov_b64_e32 v[150:151], v[144:145]
	v_mov_b64_e32 v[152:153], v[144:145]
	v_mov_b64_e32 v[154:155], v[144:145]
	v_mov_b64_e32 v[156:157], v[144:145]
	v_mov_b64_e32 v[158:159], v[144:145]
	v_mov_b32_e32 v129, v128
	v_mov_b64_e32 v[130:131], v[128:129]
	v_mov_b64_e32 v[132:133], v[128:129]
	v_mov_b64_e32 v[134:135], v[128:129]
	v_mov_b64_e32 v[136:137], v[128:129]
	s_waitcnt lgkmcnt(5)
	v_mfma_f32_32x32x16_bf16 v[144:159], v[138:141], v[218:221], v[144:159]
	v_mov_b64_e32 v[142:143], v[128:129]
	v_mov_b64_e32 v[138:139], v[128:129]
	v_mov_b64_e32 v[140:141], v[128:129]
	s_cmp_le_i32 s58, s31
	s_waitcnt lgkmcnt(4)
	v_mfma_f32_32x32x16_bf16 v[128:143], v[204:207], v[222:225], v[128:143]
	ds_read_b128 v[204:207], v199 offset:4672
	ds_read_b128 v[218:221], v199 offset:13888
	ds_read_b128 v[222:225], v189 offset:2048
	ds_read_b128 v[212:215], v189 offset:6144
	s_waitcnt lgkmcnt(5)
	v_mfma_f32_32x32x16_bf16 v[144:159], v[226:229], v[234:237], v[144:159]
	s_waitcnt lgkmcnt(4)
	v_mfma_f32_32x32x16_bf16 v[128:143], v[230:233], v[238:241], v[128:143]
	ds_read_b128 v[226:229], v199 offset:4704
	ds_read_b128 v[230:233], v199 offset:13920
	ds_read_b128 v[234:237], v189 offset:3072
	ds_read_b128 v[238:241], v189 offset:7168
	s_waitcnt lgkmcnt(5)
	v_mfma_f32_32x32x16_bf16 v[144:159], v[204:207], v[222:225], v[144:159]
	s_cbranch_scc0 .Lqk_diag1
	s_waitcnt lgkmcnt(1)
	v_mfma_f32_32x32x16_bf16 v[144:159], v[226:229], v[234:237], v[144:159]
	v_add3_u32 v243, s38, v193, v192
	ds_read_b128 v[222:225], v243 offset:23104
	ds_read_b128 v[226:229], v243 offset:23136
	v_mfma_f32_32x32x16_bf16 v[128:143], v[218:221], v[212:215], v[128:143]
	s_waitcnt lgkmcnt(2)
	v_mfma_f32_32x32x16_bf16 v[128:143], v[230:233], v[238:241], v[128:143]
	ds_read_b128 v[230:233], v243 offset:27712
	ds_read_b128 v[234:237], v243 offset:27744
	ds_read_b128 v[238:241], v243 offset:32320
	ds_read_b128 v[212:215], v243 offset:18496
	ds_read_b128 v[200:203], v243 offset:18528
	s_nop 1
